# MLA step-B pointer advances moved from loop tail into PV gaps 4-6
# speedup vs baseline: 1.0018x; 1.0018x over previous
.LBB0_287:
	v_lshl_add_u64 v[50:51], s[80:81], 0, v[222:223]
	global_load_dwordx4 v[178:181], v[50:51], off
	s_waitcnt lgkmcnt(3)
	v_mfma_f32_32x32x16_bf16 v[50:65], v[68:71], v[166:169], v[34:49]
	ds_read_b128 v[90:93], v254 offset:2048
	ds_read_b128 v[94:97], v254 offset:2560
	v_exp_f32_e32 v114, v114
	v_exp_f32_e32 v115, v115
	v_add_f32_e32 v236, v66, v114
	v_cvt_pk_bf16_f32 v114, v114, v115
	v_add_f32_e32 v237, v67, v115
	s_waitcnt lgkmcnt(4)
	v_mfma_f32_32x32x16_bf16 v[66:81], v[86:89], v[166:169], v[34:49]
	v_exp_f32_e32 v116, v116
	v_exp_f32_e32 v117, v117
	v_add_f32_e32 v236, v236, v116
	v_cvt_pk_bf16_f32 v115, v116, v117
	v_add_f32_e32 v237, v237, v117
	s_waitcnt lgkmcnt(1)
	v_mfma_f32_32x32x16_bf16 v[50:65], v[90:93], v[162:165], v[50:65]
	ds_read_b128 v[98:101], v254 offset:4096
	ds_read_b128 v[190:193], v254 offset:4608
	v_exp_f32_e32 v118, v118
	v_exp_f32_e32 v119, v119
	v_add_f32_e32 v236, v236, v118
	v_cvt_pk_bf16_f32 v116, v118, v119
	v_add_f32_e32 v237, v237, v119
	s_waitcnt lgkmcnt(2)
	v_mfma_f32_32x32x16_bf16 v[66:81], v[94:97], v[162:165], v[66:81]
	v_exp_f32_e32 v120, v120
	v_exp_f32_e32 v121, v121
	v_add_f32_e32 v236, v236, v120
	v_cvt_pk_bf16_f32 v117, v120, v121
	v_add_f32_e32 v237, v237, v121
	s_waitcnt lgkmcnt(1)
	v_mfma_f32_32x32x16_bf16 v[50:65], v[98:101], v[158:161], v[50:65]
	ds_read_b128 v[88:91], v254 offset:6144
	ds_read_b128 v[92:95], v254 offset:6656
	v_exp_f32_e32 v122, v122
	v_exp_f32_e32 v123, v123
	v_add_f32_e32 v236, v236, v122
	v_cvt_pk_bf16_f32 v118, v122, v123
	v_add_f32_e32 v237, v237, v123
	s_waitcnt lgkmcnt(2)
	v_mfma_f32_32x32x16_bf16 v[66:81], v[190:193], v[158:161], v[66:81]
	v_exp_f32_e32 v124, v124
	v_exp_f32_e32 v125, v125
	v_add_f32_e32 v236, v236, v124
	v_cvt_pk_bf16_f32 v119, v124, v125
	v_add_f32_e32 v237, v237, v125
	s_waitcnt lgkmcnt(1)
	v_mfma_f32_32x32x16_bf16 v[50:65], v[88:91], v[154:157], v[50:65]
	ds_read_b128 v[102:105], v254 offset:8192
	ds_read_b128 v[106:109], v254 offset:8704
	v_exp_f32_e32 v126, v126
	v_exp_f32_e32 v127, v127
	v_add_f32_e32 v236, v236, v126
	v_cvt_pk_bf16_f32 v120, v126, v127
	v_add_f32_e32 v237, v237, v127
	s_waitcnt lgkmcnt(2)
	v_mfma_f32_32x32x16_bf16 v[66:81], v[92:95], v[154:157], v[66:81]
	v_exp_f32_e32 v128, v128
	v_exp_f32_e32 v129, v129
	v_add_f32_e32 v236, v236, v128
	v_cvt_pk_bf16_f32 v121, v128, v129
	v_add_f32_e32 v237, v237, v129
	s_waitcnt lgkmcnt(1)
	v_mfma_f32_32x32x16_bf16 v[50:65], v[102:105], v[150:153], v[50:65]
	ds_read_b128 v[88:91], v254 offset:10240
	ds_read_b128 v[92:95], v254 offset:10752
	v_exp_f32_e32 v130, v130
	v_exp_f32_e32 v131, v131
	v_add_f32_e32 v236, v236, v130
	v_cvt_pk_bf16_f32 v84, v130, v131
	v_add_f32_e32 v237, v237, v131
	s_waitcnt lgkmcnt(2)
	v_mfma_f32_32x32x16_bf16 v[66:81], v[106:109], v[150:153], v[66:81]
	v_exp_f32_e32 v132, v132
	v_exp_f32_e32 v133, v133
	v_add_f32_e32 v236, v236, v132
	v_cvt_pk_bf16_f32 v85, v132, v133
	v_add_f32_e32 v237, v237, v133
	s_waitcnt lgkmcnt(1)
	v_mfma_f32_32x32x16_bf16 v[50:65], v[88:91], v[146:149], v[50:65]
	v_exp_f32_e32 v134, v134
	v_exp_f32_e32 v135, v135
	v_add_f32_e32 v236, v236, v134
	v_cvt_pk_bf16_f32 v86, v134, v135
	v_add_f32_e32 v237, v237, v135
	s_waitcnt lgkmcnt(0)
	v_mfma_f32_32x32x16_bf16 v[66:81], v[92:95], v[146:149], v[66:81]
	ds_read_b64_tr_b16 v[88:89], v243 offset:40960
	ds_read_b64_tr_b16 v[90:91], v243 offset:41472
	ds_read_b64_tr_b16 v[92:93], v243 offset:45056
	ds_read_b64_tr_b16 v[94:95], v243 offset:45568
	v_exp_f32_e32 v136, v136
	v_exp_f32_e32 v137, v137
	v_add_f32_e32 v236, v236, v136
	v_cvt_pk_bf16_f32 v87, v136, v137
	v_add_f32_e32 v237, v237, v137
	s_waitcnt lgkmcnt(2)
	v_mfma_f32_32x32x16_bf16 v[18:33], v[114:117], v[88:91], v[18:33]
	ds_read_b64_tr_b16 v[126:127], v243 offset:41984
	ds_read_b64_tr_b16 v[128:129], v243 offset:42496
	v_exp_f32_e32 v138, v138
	v_exp_f32_e32 v139, v139
	v_add_f32_e32 v236, v236, v138
	v_cvt_pk_bf16_f32 v122, v138, v139
	v_add_f32_e32 v237, v237, v139
	s_waitcnt lgkmcnt(2)
	v_mfma_f32_32x32x16_bf16 v[2:17], v[114:117], v[92:95], v[2:17]
	ds_read_b64_tr_b16 v[88:89], v243 offset:46080
	ds_read_b64_tr_b16 v[90:91], v243 offset:46592
	v_exp_f32_e32 v140, v140
	v_exp_f32_e32 v141, v141
	v_add_f32_e32 v236, v236, v140
	v_cvt_pk_bf16_f32 v123, v140, v141
	v_add_f32_e32 v237, v237, v141
	s_waitcnt lgkmcnt(2)
	v_mfma_f32_32x32x16_bf16 v[18:33], v[118:121], v[126:129], v[18:33]
	ds_read_b64_tr_b16 v[92:93], v243 offset:43008
	ds_read_b64_tr_b16 v[94:95], v243 offset:43520
	v_exp_f32_e32 v142, v142
	v_exp_f32_e32 v143, v143
	v_add_f32_e32 v236, v236, v142
	v_cvt_pk_bf16_f32 v124, v142, v143
	v_add_f32_e32 v237, v237, v143
	s_waitcnt lgkmcnt(2)
	v_mfma_f32_32x32x16_bf16 v[2:17], v[118:121], v[88:91], v[2:17]
	ds_read_b64_tr_b16 v[114:115], v243 offset:47104
	ds_read_b64_tr_b16 v[116:117], v243 offset:47616
	v_exp_f32_e32 v144, v144
	v_exp_f32_e32 v145, v145
	v_add_f32_e32 v130, v236, v144
	v_cvt_pk_bf16_f32 v125, v144, v145
	v_add_f32_e32 v131, v237, v145
	s_waitcnt lgkmcnt(2)
	v_mfma_f32_32x32x16_bf16 v[18:33], v[84:87], v[92:95], v[18:33]
	ds_read_b64_tr_b16 v[88:89], v243 offset:44032
	ds_read_b64_tr_b16 v[90:91], v243 offset:44544
	v_max_f32_e32 v83, v50, v50
	v_max_f32_e32 v83, 0xf149f2ca, v83
	v_max3_f32 v96, v66, s25, v67
	v_max3_f32 v83, v83, v51, v52
	v_max3_f32 v96, v96, v68, v69
	v_lshl_add_u64 v[218:219], v[218:219], 0, s[38:39]
	s_waitcnt lgkmcnt(2)
	v_mfma_f32_32x32x16_bf16 v[2:17], v[84:87], v[114:117], v[2:17]
	ds_read_b64_tr_b16 v[92:93], v243 offset:48128
	ds_read_b64_tr_b16 v[94:95], v243 offset:48640
	v_max3_f32 v83, v83, v53, v54
	v_max3_f32 v96, v96, v70, v71
	v_max3_f32 v83, v83, v55, v56
	v_max3_f32 v96, v96, v72, v73
	v_lshl_add_u64 v[220:221], v[220:221], 0, s[82:83]
	s_waitcnt lgkmcnt(2)
	v_mfma_f32_32x32x16_bf16 v[18:33], v[122:125], v[88:91], v[18:33]
	v_max3_f32 v83, v83, v57, v58
	v_max3_f32 v96, v96, v74, v75
	v_max3_f32 v83, v83, v59, v60
	v_max3_f32 v96, v96, v76, v77
	v_lshl_add_u64 v[222:223], v[222:223], 0, s[82:83]
	s_waitcnt lgkmcnt(0)
	v_mfma_f32_32x32x16_bf16 v[2:17], v[122:125], v[92:95], v[2:17]
	v_max3_f32 v83, v83, v61, v62
	v_max3_f32 v96, v96, v78, v79
	v_max3_f32 v83, v83, v63, v64
	v_max3_f32 v96, v96, v80, v81
	s_add_i32 s36, s36, 2
	v_max3_f32 v83, v83, v65, v96
	s_cmpk_gt_u32 s36, 0x7d
	v_lshl_add_u64 v[224:225], v[224:225], 0, s[82:83]
	s_barrier
	s_cbranch_scc1 .LBB0_305
